# latent attention item: final PV MFMA ladder fed by fragments read five ahead; prologue load batches overlapped
# baseline (speedup 1.0000x reference)
.LBB0_214:
	v_add_u32_e32 v68, v174, v176
	v_add_u32_e32 v202, v174, v175
	v_add_u32_e32 v203, v174, v173
	v_add_u32_e32 v204, v174, v171
	s_cmp_eq_u32 s59, 1
	ds_read_b128 v[64:67], v68 offset:49152
	ds_read_b128 v[214:217], v68 offset:53248
	ds_read_b128 v[218:221], v68 offset:57344
	ds_read_b128 v[246:249], v68 offset:61440
	ds_read_b128 v[236:239], v202 offset:49152
	s_waitcnt lgkmcnt(4)
	v_mfma_f32_32x32x16_bf16 v[48:63], v[64:67], v[148:151], v[48:63]
	ds_read_b128 v[64:67], v202 offset:53248
	s_waitcnt lgkmcnt(4)
	v_mfma_f32_32x32x16_bf16 v[32:47], v[214:217], v[148:151], v[32:47]
	ds_read_b128 v[214:217], v202 offset:57344
	s_waitcnt lgkmcnt(4)
	v_mfma_f32_32x32x16_bf16 v[16:31], v[218:221], v[148:151], v[16:31]
	ds_read_b128 v[218:221], v202 offset:61440
	s_waitcnt lgkmcnt(4)
	v_mfma_f32_32x32x16_bf16 v[0:15], v[246:249], v[148:151], v[0:15]
	ds_read_b128 v[246:249], v203 offset:49152
	s_waitcnt lgkmcnt(4)
	v_mfma_f32_32x32x16_bf16 v[48:63], v[236:239], v[144:147], v[48:63]
	ds_read_b128 v[236:239], v203 offset:53248
	s_waitcnt lgkmcnt(4)
	v_mfma_f32_32x32x16_bf16 v[32:47], v[64:67], v[144:147], v[32:47]
	ds_read_b128 v[64:67], v203 offset:57344
	s_waitcnt lgkmcnt(4)
	v_mfma_f32_32x32x16_bf16 v[16:31], v[214:217], v[144:147], v[16:31]
	ds_read_b128 v[214:217], v203 offset:61440
	s_waitcnt lgkmcnt(4)
	v_mfma_f32_32x32x16_bf16 v[0:15], v[218:221], v[144:147], v[0:15]
	ds_read_b128 v[218:221], v204 offset:49152
	s_waitcnt lgkmcnt(4)
	v_mfma_f32_32x32x16_bf16 v[48:63], v[246:249], v[140:143], v[48:63]
	ds_read_b128 v[246:249], v204 offset:53248
	s_waitcnt lgkmcnt(4)
	v_mfma_f32_32x32x16_bf16 v[32:47], v[236:239], v[140:143], v[32:47]
	ds_read_b128 v[236:239], v204 offset:57344
	s_waitcnt lgkmcnt(4)
	v_mfma_f32_32x32x16_bf16 v[16:31], v[64:67], v[140:143], v[16:31]
	ds_read_b128 v[64:67], v204 offset:61440
	s_waitcnt lgkmcnt(4)
	v_mfma_f32_32x32x16_bf16 v[0:15], v[214:217], v[140:143], v[0:15]
	s_waitcnt lgkmcnt(3)
	v_mfma_f32_32x32x16_bf16 v[48:63], v[218:221], v[136:139], v[48:63]
	s_waitcnt lgkmcnt(2)
	v_mfma_f32_32x32x16_bf16 v[32:47], v[246:249], v[136:139], v[32:47]
	s_waitcnt lgkmcnt(1)
	v_mfma_f32_32x32x16_bf16 v[16:31], v[236:239], v[136:139], v[16:31]
	s_waitcnt lgkmcnt(0)
	v_mfma_f32_32x32x16_bf16 v[0:15], v[64:67], v[136:139], v[0:15]
	ds_bpermute_b32 v64, v164, v168
	s_waitcnt lgkmcnt(0)
	v_add_f32_e32 v64, v168, v64
	v_div_scale_f32 v65, s[0:1], v64, v64, 1.0
	v_rcp_f32_e32 v66, v65
	s_nop 0
	v_fma_f32 v67, -v65, v66, 1.0
	v_fmac_f32_e32 v66, v67, v66
	v_div_scale_f32 v67, vcc, 1.0, v64, 1.0
	v_mul_f32_e32 v68, v67, v66
	v_fma_f32 v69, -v65, v68, v67
	v_fmac_f32_e32 v68, v69, v66
	v_fma_f32 v65, -v65, v68, v67
	v_div_fmas_f32 v65, v65, v66, v68
	v_div_fixup_f32 v64, v65, v64, 1.0
	s_cbranch_scc0 .LBB0_216
	s_lshl_b32 s0, s58, 14
	s_add_i32 s0, s0, 0
	v_lshl_add_u32 v66, v166, 2, s0
	v_mul_f32_e32 v65, v48, v64
	v_add_u32_e32 v66, 0x10000, v66
	v_mul_f32_e32 v67, v49, v64
	ds_write2st64_b32 v66, v65, v67 offset1:1
	v_mul_f32_e32 v65, v50, v64
	v_mul_f32_e32 v67, v51, v64
	ds_write2st64_b32 v66, v65, v67 offset0:2 offset1:3
	v_mul_f32_e32 v65, v52, v64
	v_mul_f32_e32 v67, v53, v64
	ds_write2st64_b32 v66, v65, v67 offset0:4 offset1:5
	v_mul_f32_e32 v65, v54, v64
	v_mul_f32_e32 v67, v55, v64
	ds_write2st64_b32 v66, v65, v67 offset0:6 offset1:7
	v_mul_f32_e32 v65, v56, v64
	v_mul_f32_e32 v67, v57, v64
	ds_write2st64_b32 v66, v65, v67 offset0:8 offset1:9
	v_mul_f32_e32 v65, v58, v64
	v_mul_f32_e32 v67, v59, v64
	ds_write2st64_b32 v66, v65, v67 offset0:10 offset1:11
	v_mul_f32_e32 v65, v60, v64
	v_mul_f32_e32 v67, v61, v64
	ds_write2st64_b32 v66, v65, v67 offset0:12 offset1:13
	v_mul_f32_e32 v65, v62, v64
	v_mul_f32_e32 v67, v63, v64
	ds_write2st64_b32 v66, v65, v67 offset0:14 offset1:15
	v_mul_f32_e32 v65, v32, v64
	v_mul_f32_e32 v67, v33, v64
	ds_write2st64_b32 v66, v65, v67 offset0:16 offset1:17
	v_mul_f32_e32 v65, v34, v64
	v_mul_f32_e32 v67, v35, v64
	ds_write2st64_b32 v66, v65, v67 offset0:18 offset1:19
	v_mul_f32_e32 v65, v36, v64
	v_mul_f32_e32 v67, v37, v64
	ds_write2st64_b32 v66, v65, v67 offset0:20 offset1:21
	v_mul_f32_e32 v65, v38, v64
	v_mul_f32_e32 v67, v39, v64
	ds_write2st64_b32 v66, v65, v67 offset0:22 offset1:23
	v_mul_f32_e32 v65, v40, v64
	v_mul_f32_e32 v67, v41, v64
	ds_write2st64_b32 v66, v65, v67 offset0:24 offset1:25
	v_mul_f32_e32 v65, v42, v64
	v_mul_f32_e32 v67, v43, v64
	ds_write2st64_b32 v66, v65, v67 offset0:26 offset1:27
	v_mul_f32_e32 v65, v44, v64
	v_mul_f32_e32 v67, v45, v64
	ds_write2st64_b32 v66, v65, v67 offset0:28 offset1:29
	v_mul_f32_e32 v65, v46, v64
	v_mul_f32_e32 v67, v47, v64
	ds_write2st64_b32 v66, v65, v67 offset0:30 offset1:31
	v_mul_f32_e32 v65, v16, v64
	v_mul_f32_e32 v67, v17, v64
	ds_write2st64_b32 v66, v65, v67 offset0:32 offset1:33
	v_mul_f32_e32 v65, v18, v64
	v_mul_f32_e32 v67, v19, v64
	ds_write2st64_b32 v66, v65, v67 offset0:34 offset1:35
	v_mul_f32_e32 v65, v20, v64
	v_mul_f32_e32 v67, v21, v64
	ds_write2st64_b32 v66, v65, v67 offset0:36 offset1:37
	v_mul_f32_e32 v65, v22, v64
	v_mul_f32_e32 v67, v23, v64
	ds_write2st64_b32 v66, v65, v67 offset0:38 offset1:39
	v_mul_f32_e32 v65, v24, v64
	v_mul_f32_e32 v67, v25, v64
	ds_write2st64_b32 v66, v65, v67 offset0:40 offset1:41
	v_mul_f32_e32 v65, v26, v64
	v_mul_f32_e32 v67, v27, v64
	ds_write2st64_b32 v66, v65, v67 offset0:42 offset1:43
	v_mul_f32_e32 v65, v28, v64
	v_mul_f32_e32 v67, v29, v64
	ds_write2st64_b32 v66, v65, v67 offset0:44 offset1:45
	v_mul_f32_e32 v65, v30, v64
	v_mul_f32_e32 v67, v31, v64
	ds_write2st64_b32 v66, v65, v67 offset0:46 offset1:47
	v_mul_f32_e32 v65, v0, v64
	v_mul_f32_e32 v67, v1, v64
	ds_write2st64_b32 v66, v65, v67 offset0:48 offset1:49
	v_mul_f32_e32 v65, v2, v64
	v_mul_f32_e32 v67, v3, v64
	ds_write2st64_b32 v66, v65, v67 offset0:50 offset1:51
	v_mul_f32_e32 v65, v4, v64
	v_mul_f32_e32 v67, v5, v64
	ds_write2st64_b32 v66, v65, v67 offset0:52 offset1:53
	v_mul_f32_e32 v65, v6, v64
	v_mul_f32_e32 v67, v7, v64
	ds_write2st64_b32 v66, v65, v67 offset0:54 offset1:55
	v_mul_f32_e32 v65, v8, v64
	v_mul_f32_e32 v67, v9, v64
	ds_write2st64_b32 v66, v65, v67 offset0:56 offset1:57
	v_mul_f32_e32 v65, v10, v64
	v_mul_f32_e32 v67, v11, v64
	ds_write2st64_b32 v66, v65, v67 offset0:58 offset1:59
	v_mul_f32_e32 v65, v12, v64
	v_mul_f32_e32 v67, v13, v64
	ds_write2st64_b32 v66, v65, v67 offset0:60 offset1:61
	v_mul_f32_e32 v65, v14, v64
	v_mul_f32_e32 v67, v15, v64
	ds_write2st64_b32 v66, v65, v67 offset0:62 offset1:63
